# attention loops: staging LDS stores / global loads issued one per MFMA gap instead of as a block
# speedup vs baseline: 1.0883x; 1.0172x over previous
; #define LAS __attribute__((address_space(3)))
; template <int DQK, int DV, int FLAGS, int qp, int kp, int vts, int op> ...
;     ...
;             for (int c = 0; c < ND0 / 2; ++c) {
;                 if (c + 1 < ND0 / 2) {
; #pragma unroll
;                     for (int i = 0; i < 2; ++i) { kf[(c + 1) & 1][2 * i] = *(const LAS bf16x8*)(kb + (2 * c + 2 + i) * 32); kf[(c + 1) & 1][2 * i + 1] = *(const LAS bf16x8*)(kb + 32 * KROW + (2 * c + 2 + i) * 32); }
;                 }
; #pragma unroll
;                 for (int i = 0; i < 2; ++i) {
;                     p0 = __builtin_amdgcn_mfma_f32_32x32x16_bf16(kf[c & 1][2 * i], qr[2 * c + i], p0, 0, 0, 0);
;                     p1 = __builtin_amdgcn_mfma_f32_32x32x16_bf16(kf[c & 1][2 * i + 1], qr[2 * c + i], p1, 0, 0, 0);
;                 }
;                 __builtin_amdgcn_sched_barrier(0);
;             }
;             if (more) ATT_GLOAD((FLAGS & AF_REV) ? t - 1 : t + 1);
;     ...
;             f32x2 rs2 = {0.f, 0.f};
; #pragma unroll
;             for (int r = 0; r < 16; ++r) { p0[r] = __builtin_amdgcn_exp2f(p0[r]); p1[r] = __builtin_amdgcn_exp2f(p1[r]); }
; #pragma unroll
;             for (int r = 0; r < 16; r += 2) { rs2 += (f32x2){p0[r], p0[r + 1]}; rs2 += (f32x2){p1[r], p1[r + 1]}; }
;             l += rs2.x + rs2.y;
;             bf16x8 pf[4];
;             pf[0] = pack_bf16x8(p0, 0); pf[1] = pack_bf16x8(p0, 8); pf[2] = pack_bf16x8(p1, 0); pf[3] = pack_bf16x8(p1, 8);
;             __builtin_amdgcn_sched_barrier(0);
; #pragma unroll
;             for (int d = 0; d < NDB; ++d) {
;                 if (d + 1 < NDB) {
; #pragma unroll
;                     for (int ks = 0; ks < 4; ++ks) vf[(d + 1) & 1][ks] = *(const LAS bf16x8*)(vb + (d + 1) * 32 * VROW + ks * 32);
;                 }
; #pragma unroll
;                 for (int ks = 0; ks < 4; ++ks) o[d] = __builtin_amdgcn_mfma_f32_32x32x16_bf16(vf[d & 1][ks], pf[ks], o[d], 0, 0, 0);
;                 __builtin_amdgcn_sched_barrier(0);
;             }
;         }
;         if (skip && more) ATT_GLOAD((FLAGS & AF_REV) ? t - 1 : t + 1);
;         if (more) ATT_LSTORE(cur ^ 1);
.Lq_top0:
	s_cmp_eq_u32 s3, 0
	s_cbranch_scc1 .Lq_gen0
	s_add_i32 s13, s3, 1
	s_cmp_ge_i32 s13, s20
	s_cbranch_scc1 .Lq_gen0
	s_add_i32 s12, s3, 1
	s_and_b32 s12, s12, 3
	s_mulk_i32 s12, 0x5800
	v_add3_u32 v206, s12, v169, v0
	ds_read_b128 v[96:99], v206
	ds_read_b128 v[104:107], v206 offset:6656
	ds_read_b128 v[100:103], v206 offset:32
	ds_read_b128 v[108:111], v206 offset:6688
	ds_read_b128 v[112:115], v206 offset:64
	ds_read_b128 v[120:123], v206 offset:6720
	ds_read_b128 v[116:119], v206 offset:96
	ds_read_b128 v[124:127], v206 offset:6752
	s_and_b32 s16, s3, 3
	s_mulk_i32 s16, 0x5800
	v_add3_u32 v207, s16, v171, v0
	v_mfma_f32_32x32x16_bf16 v[32:47], v[152:155], v[214:217], v[32:47]
	v_exp_f32_e32 v64, v64
	v_exp_f32_e32 v65, v65
	v_mfma_f32_32x32x16_bf16 v[16:31], v[188:191], v[214:217], v[16:31]
	v_exp_f32_e32 v80, v80
	v_exp_f32_e32 v81, v81
	v_mov_b32_e32 v204, v64
	v_mov_b32_e32 v205, v65
	s_add_i32 s12, s3, 2
	s_and_b32 s16, s12, 3
	s_mulk_i32 s16, 0x5800
	v_add_u32_e32 v209, s16, v14
	s_waitcnt vmcnt(0)
	ds_write_b128 v209, v[140:143]
	v_mfma_f32_32x32x16_bf16 v[32:47], v[156:159], v[218:221], v[32:47]
	v_exp_f32_e32 v66, v66
	v_exp_f32_e32 v67, v67
	v_add_f32_e32 v204, v80, v204
	v_add_f32_e32 v205, v81, v205
	v_add_u32_e32 v210, s16, v174
	ds_write_b128 v210, v[148:151] offset:13312
	v_mfma_f32_32x32x16_bf16 v[16:31], v[192:195], v[218:221], v[16:31]
	v_exp_f32_e32 v82, v82
	v_exp_f32_e32 v83, v83
	v_add_f32_e32 v204, v66, v204
	v_add_f32_e32 v205, v67, v205
	v_add_u32_e32 v211, s16, v172
	s_and_saveexec_b64 s[14:15], s[10:11]
	ds_write_b128 v211, v[144:147]
	s_or_b64 exec, exec, s[14:15]
	v_mfma_f32_32x32x16_bf16 v[32:47], v[160:163], v[222:225], v[32:47]
	v_exp_f32_e32 v68, v68
	v_exp_f32_e32 v69, v69
	v_add_f32_e32 v204, v82, v204
	v_add_f32_e32 v205, v83, v205
	s_add_i32 s12, s3, 3
	s_cmp_ge_i32 s12, s2
	s_cbranch_scc1 .Lq_ng0_s0
	s_and_saveexec_b64 s[14:15], s[10:11]
	global_load_dwordx4 v[144:147], v[180:181], off
	s_or_b64 exec, exec, s[14:15]
	v_lshl_add_u64 v[180:181], v[180:181], 0, s[96:97]
.Lq_ng0_s0:
	v_mfma_f32_32x32x16_bf16 v[16:31], v[196:199], v[222:225], v[16:31]
	v_exp_f32_e32 v84, v84
	v_exp_f32_e32 v85, v85
	v_add_f32_e32 v204, v68, v204
	v_add_f32_e32 v205, v69, v205
	s_add_i32 s12, s3, 3
	s_cmp_ge_i32 s12, s2
	s_cbranch_scc1 .Lq_ng1_s0
	global_load_dwordx4 v[140:143], v[178:179], off
	v_lshl_add_u64 v[178:179], v[178:179], 0, s[96:97]
.Lq_ng1_s0:
	v_mfma_f32_32x32x16_bf16 v[32:47], v[164:167], v[226:229], v[32:47]
	v_exp_f32_e32 v70, v70
	v_exp_f32_e32 v71, v71
	v_add_f32_e32 v204, v84, v204
	v_add_f32_e32 v205, v85, v205
	s_add_i32 s12, s3, 3
	s_cmp_ge_i32 s12, s2
	s_cbranch_scc1 .Lq_ng2_s0
	global_load_dwordx4 v[148:151], v[176:177], off
	s_mov_b64 s[14:15], 0x80
	v_lshl_add_u64 v[176:177], v[176:177], 0, s[14:15]
.Lq_ng2_s0:
	v_mfma_f32_32x32x16_bf16 v[16:31], v[200:203], v[226:229], v[16:31]
	v_exp_f32_e32 v86, v86
	v_exp_f32_e32 v87, v87
	v_add_f32_e32 v204, v70, v204
	v_add_f32_e32 v205, v71, v205
	ds_read_b128 v[152:155], v207 offset:13312
	ds_read_b128 v[156:159], v207 offset:13344
	ds_read_b128 v[160:163], v207 offset:13376
	ds_read_b128 v[164:167], v207 offset:13408
	s_waitcnt lgkmcnt(8)
	v_mfma_f32_32x32x16_bf16 v[214:229], v[96:99], v[2:5], v[48:63]
	v_exp_f32_e32 v72, v72
	v_exp_f32_e32 v73, v73
	v_add_f32_e32 v204, v86, v204
	v_add_f32_e32 v205, v87, v205
	v_mfma_f32_32x32x16_bf16 v[230:245], v[104:107], v[2:5], v[48:63]
	v_exp_f32_e32 v88, v88
	v_exp_f32_e32 v89, v89
	v_add_f32_e32 v204, v72, v204
	v_add_f32_e32 v205, v73, v205
	v_mfma_f32_32x32x16_bf16 v[214:229], v[100:103], v[6:9], v[214:229]
	v_exp_f32_e32 v74, v74
	v_exp_f32_e32 v75, v75
	v_add_f32_e32 v204, v88, v204
	v_add_f32_e32 v205, v89, v205
	v_mfma_f32_32x32x16_bf16 v[230:245], v[108:111], v[6:9], v[230:245]
	v_exp_f32_e32 v90, v90
	v_exp_f32_e32 v91, v91
	v_add_f32_e32 v204, v74, v204
	v_add_f32_e32 v205, v75, v205
	ds_read_b128 v[96:99], v206 offset:128
	ds_read_b128 v[104:107], v206 offset:6784
	ds_read_b128 v[100:103], v206 offset:160
	ds_read_b128 v[108:111], v206 offset:6816
	s_waitcnt lgkmcnt(8)
	v_mfma_f32_32x32x16_bf16 v[214:229], v[112:115], v[10:13], v[214:229]
	v_exp_f32_e32 v76, v76
	v_exp_f32_e32 v77, v77
	v_add_f32_e32 v204, v90, v204
	v_add_f32_e32 v205, v91, v205
	v_mfma_f32_32x32x16_bf16 v[230:245], v[120:123], v[10:13], v[230:245]
	v_exp_f32_e32 v92, v92
	v_exp_f32_e32 v93, v93
	v_add_f32_e32 v204, v76, v204
	v_add_f32_e32 v205, v77, v205
	v_mfma_f32_32x32x16_bf16 v[214:229], v[116:119], v[128:131], v[214:229]
	v_exp_f32_e32 v78, v78
	v_exp_f32_e32 v79, v79
	v_add_f32_e32 v204, v92, v204
	v_add_f32_e32 v205, v93, v205
	v_mfma_f32_32x32x16_bf16 v[230:245], v[124:127], v[128:131], v[230:245]
	v_exp_f32_e32 v94, v94
	v_exp_f32_e32 v95, v95
	v_add_f32_e32 v204, v78, v204
	v_add_f32_e32 v205, v79, v205
	ds_read_b128 v[188:191], v207 offset:17920
	ds_read_b128 v[192:195], v207 offset:17952
	ds_read_b128 v[196:199], v207 offset:17984
	ds_read_b128 v[200:203], v207 offset:18016
	s_waitcnt lgkmcnt(4)
	v_mfma_f32_32x32x16_bf16 v[214:229], v[96:99], v[132:135], v[214:229]
	s_nop 0
	v_add_f32_e32 v204, v94, v204
	v_add_f32_e32 v205, v95, v205
	v_cvt_pk_bf16_f32 v64, v64, v65
	v_cvt_pk_bf16_f32 v65, v66, v67
	v_cvt_pk_bf16_f32 v66, v68, v69
	v_mfma_f32_32x32x16_bf16 v[230:245], v[104:107], v[132:135], v[230:245]
	v_cvt_pk_bf16_f32 v67, v70, v71
	v_cvt_pk_bf16_f32 v68, v72, v73
	v_cvt_pk_bf16_f32 v69, v74, v75
	v_cvt_pk_bf16_f32 v70, v76, v77
	v_cvt_pk_bf16_f32 v71, v78, v79
	v_mfma_f32_32x32x16_bf16 v[214:229], v[100:103], v[136:139], v[214:229]
	v_cvt_pk_bf16_f32 v72, v80, v81
	v_cvt_pk_bf16_f32 v73, v82, v83
	v_cvt_pk_bf16_f32 v74, v84, v85
	v_cvt_pk_bf16_f32 v75, v86, v87
	v_cvt_pk_bf16_f32 v76, v88, v89
	v_mfma_f32_32x32x16_bf16 v[230:245], v[108:111], v[136:139], v[230:245]
	v_cvt_pk_bf16_f32 v77, v90, v91
	v_cvt_pk_bf16_f32 v78, v92, v93
	v_cvt_pk_bf16_f32 v79, v94, v95
	v_add_f32_e32 v208, v204, v205
	v_add_f32_e32 v175, v175, v208
	s_branch .Lq_tailb0

; #define LAS __attribute__((address_space(3)))
; template <int DQK, int DV, int FLAGS, int qp, int kp, int vts, int op> ...
;     ...
;             for (int c = 0; c < ND0 / 2; ++c) {
;                 if (c + 1 < ND0 / 2) {
; #pragma unroll
;                     for (int i = 0; i < 2; ++i) { kf[(c + 1) & 1][2 * i] = *(const LAS bf16x8*)(kb + (2 * c + 2 + i) * 32); kf[(c + 1) & 1][2 * i + 1] = *(const LAS bf16x8*)(kb + 32 * KROW + (2 * c + 2 + i) * 32); }
;                 }
; #pragma unroll
;                 for (int i = 0; i < 2; ++i) {
;                     p0 = __builtin_amdgcn_mfma_f32_32x32x16_bf16(kf[c & 1][2 * i], qr[2 * c + i], p0, 0, 0, 0);
;                     p1 = __builtin_amdgcn_mfma_f32_32x32x16_bf16(kf[c & 1][2 * i + 1], qr[2 * c + i], p1, 0, 0, 0);
;                 }
;                 __builtin_amdgcn_sched_barrier(0);
;             }
;             if (more) ATT_GLOAD((FLAGS & AF_REV) ? t - 1 : t + 1);
;     ...
;             f32x2 rs2 = {0.f, 0.f};
; #pragma unroll
;             for (int r = 0; r < 16; ++r) { p0[r] = __builtin_amdgcn_exp2f(p0[r]); p1[r] = __builtin_amdgcn_exp2f(p1[r]); }
; #pragma unroll
;             for (int r = 0; r < 16; r += 2) { rs2 += (f32x2){p0[r], p0[r + 1]}; rs2 += (f32x2){p1[r], p1[r + 1]}; }
;             l += rs2.x + rs2.y;
;             bf16x8 pf[4];
;             pf[0] = pack_bf16x8(p0, 0); pf[1] = pack_bf16x8(p0, 8); pf[2] = pack_bf16x8(p1, 0); pf[3] = pack_bf16x8(p1, 8);
;             __builtin_amdgcn_sched_barrier(0);
; #pragma unroll
;             for (int d = 0; d < NDB; ++d) {
;                 if (d + 1 < NDB) {
; #pragma unroll
;                     for (int ks = 0; ks < 4; ++ks) vf[(d + 1) & 1][ks] = *(const LAS bf16x8*)(vb + (d + 1) * 32 * VROW + ks * 32);
;                 }
; #pragma unroll
;                 for (int ks = 0; ks < 4; ++ks) o[d] = __builtin_amdgcn_mfma_f32_32x32x16_bf16(vf[d & 1][ks], pf[ks], o[d], 0, 0, 0);
;                 __builtin_amdgcn_sched_barrier(0);
;             }
;         }
;         if (skip && more) ATT_GLOAD((FLAGS & AF_REV) ? t - 1 : t + 1);
;         if (more) ATT_LSTORE(cur ^ 1);
.Lq_top1:
	s_cmp_eq_u32 s3, 0
	s_cbranch_scc1 .Lq_gen1
	s_add_i32 s13, s3, 1
	s_cmp_ge_i32 s13, s20
	s_cbranch_scc1 .Lq_gen1
	s_add_i32 s12, s3, 1
	s_and_b32 s12, s12, 3
	s_mulk_i32 s12, 0x5800
	v_add3_u32 v206, s12, v169, v0
	ds_read_b128 v[96:99], v206
	ds_read_b128 v[104:107], v206 offset:6656
	ds_read_b128 v[100:103], v206 offset:32
	ds_read_b128 v[108:111], v206 offset:6688
	ds_read_b128 v[112:115], v206 offset:64
	ds_read_b128 v[120:123], v206 offset:6720
	ds_read_b128 v[116:119], v206 offset:96
	ds_read_b128 v[124:127], v206 offset:6752
	s_and_b32 s16, s3, 3
	s_mulk_i32 s16, 0x5800
	v_add3_u32 v207, s16, v171, v0
	v_mfma_f32_32x32x16_bf16 v[32:47], v[152:155], v[64:67], v[32:47]
	v_exp_f32_e32 v214, v214
	v_exp_f32_e32 v215, v215
	v_mfma_f32_32x32x16_bf16 v[16:31], v[188:191], v[64:67], v[16:31]
	v_exp_f32_e32 v230, v230
	v_exp_f32_e32 v231, v231
	v_mov_b32_e32 v204, v214
	v_mov_b32_e32 v205, v215
	s_add_i32 s12, s3, 2
	s_and_b32 s16, s12, 3
	s_mulk_i32 s16, 0x5800
	v_add_u32_e32 v209, s16, v14
	s_waitcnt vmcnt(0)
	ds_write_b128 v209, v[140:143]
	v_mfma_f32_32x32x16_bf16 v[32:47], v[156:159], v[68:71], v[32:47]
	v_exp_f32_e32 v216, v216
	v_exp_f32_e32 v217, v217
	v_add_f32_e32 v204, v230, v204
	v_add_f32_e32 v205, v231, v205
	v_add_u32_e32 v210, s16, v174
	ds_write_b128 v210, v[148:151] offset:13312
	v_mfma_f32_32x32x16_bf16 v[16:31], v[192:195], v[68:71], v[16:31]
	v_exp_f32_e32 v232, v232
	v_exp_f32_e32 v233, v233
	v_add_f32_e32 v204, v216, v204
	v_add_f32_e32 v205, v217, v205
	v_add_u32_e32 v211, s16, v172
	s_and_saveexec_b64 s[14:15], s[10:11]
	ds_write_b128 v211, v[144:147]
	s_or_b64 exec, exec, s[14:15]
	v_mfma_f32_32x32x16_bf16 v[32:47], v[160:163], v[72:75], v[32:47]
	v_exp_f32_e32 v218, v218
	v_exp_f32_e32 v219, v219
	v_add_f32_e32 v204, v232, v204
	v_add_f32_e32 v205, v233, v205
	s_add_i32 s12, s3, 3
	s_cmp_ge_i32 s12, s2
	s_cbranch_scc1 .Lq_ng0_s1
	s_and_saveexec_b64 s[14:15], s[10:11]
	global_load_dwordx4 v[144:147], v[180:181], off
	s_or_b64 exec, exec, s[14:15]
	v_lshl_add_u64 v[180:181], v[180:181], 0, s[96:97]
.Lq_ng0_s1:
	v_mfma_f32_32x32x16_bf16 v[16:31], v[196:199], v[72:75], v[16:31]
	v_exp_f32_e32 v234, v234
	v_exp_f32_e32 v235, v235
	v_add_f32_e32 v204, v218, v204
	v_add_f32_e32 v205, v219, v205
	s_add_i32 s12, s3, 3
	s_cmp_ge_i32 s12, s2
	s_cbranch_scc1 .Lq_ng1_s1
	global_load_dwordx4 v[140:143], v[178:179], off
	v_lshl_add_u64 v[178:179], v[178:179], 0, s[96:97]
.Lq_ng1_s1:
	v_mfma_f32_32x32x16_bf16 v[32:47], v[164:167], v[76:79], v[32:47]
	v_exp_f32_e32 v220, v220
	v_exp_f32_e32 v221, v221
	v_add_f32_e32 v204, v234, v204
	v_add_f32_e32 v205, v235, v205
	s_add_i32 s12, s3, 3
	s_cmp_ge_i32 s12, s2
	s_cbranch_scc1 .Lq_ng2_s1
	global_load_dwordx4 v[148:151], v[176:177], off
	s_mov_b64 s[14:15], 0x80
	v_lshl_add_u64 v[176:177], v[176:177], 0, s[14:15]
.Lq_ng2_s1:
	v_mfma_f32_32x32x16_bf16 v[16:31], v[200:203], v[76:79], v[16:31]
	v_exp_f32_e32 v236, v236
	v_exp_f32_e32 v237, v237
	v_add_f32_e32 v204, v220, v204
	v_add_f32_e32 v205, v221, v205
	ds_read_b128 v[152:155], v207 offset:13312
	ds_read_b128 v[156:159], v207 offset:13344
	ds_read_b128 v[160:163], v207 offset:13376
	ds_read_b128 v[164:167], v207 offset:13408
	s_waitcnt lgkmcnt(8)
	v_mfma_f32_32x32x16_bf16 v[64:79], v[96:99], v[2:5], v[48:63]
	v_exp_f32_e32 v222, v222
	v_exp_f32_e32 v223, v223
	v_add_f32_e32 v204, v236, v204
	v_add_f32_e32 v205, v237, v205
	v_mfma_f32_32x32x16_bf16 v[80:95], v[104:107], v[2:5], v[48:63]
	v_exp_f32_e32 v238, v238
	v_exp_f32_e32 v239, v239
	v_add_f32_e32 v204, v222, v204
	v_add_f32_e32 v205, v223, v205
	v_mfma_f32_32x32x16_bf16 v[64:79], v[100:103], v[6:9], v[64:79]
	v_exp_f32_e32 v224, v224
	v_exp_f32_e32 v225, v225
	v_add_f32_e32 v204, v238, v204
	v_add_f32_e32 v205, v239, v205
	v_mfma_f32_32x32x16_bf16 v[80:95], v[108:111], v[6:9], v[80:95]
	v_exp_f32_e32 v240, v240
	v_exp_f32_e32 v241, v241
	v_add_f32_e32 v204, v224, v204
	v_add_f32_e32 v205, v225, v205
	ds_read_b128 v[96:99], v206 offset:128
	ds_read_b128 v[104:107], v206 offset:6784
	ds_read_b128 v[100:103], v206 offset:160
	ds_read_b128 v[108:111], v206 offset:6816
	s_waitcnt lgkmcnt(8)
	v_mfma_f32_32x32x16_bf16 v[64:79], v[112:115], v[10:13], v[64:79]
	v_exp_f32_e32 v226, v226
	v_exp_f32_e32 v227, v227
	v_add_f32_e32 v204, v240, v204
	v_add_f32_e32 v205, v241, v205
	v_mfma_f32_32x32x16_bf16 v[80:95], v[120:123], v[10:13], v[80:95]
	v_exp_f32_e32 v242, v242
	v_exp_f32_e32 v243, v243
	v_add_f32_e32 v204, v226, v204
	v_add_f32_e32 v205, v227, v205
	v_mfma_f32_32x32x16_bf16 v[64:79], v[116:119], v[128:131], v[64:79]
	v_exp_f32_e32 v228, v228
	v_exp_f32_e32 v229, v229
	v_add_f32_e32 v204, v242, v204
	v_add_f32_e32 v205, v243, v205
	v_mfma_f32_32x32x16_bf16 v[80:95], v[124:127], v[128:131], v[80:95]
	v_exp_f32_e32 v244, v244
	v_exp_f32_e32 v245, v245
	v_add_f32_e32 v204, v228, v204
	v_add_f32_e32 v205, v229, v205
	ds_read_b128 v[188:191], v207 offset:17920
	ds_read_b128 v[192:195], v207 offset:17952
	ds_read_b128 v[196:199], v207 offset:17984
	ds_read_b128 v[200:203], v207 offset:18016
	s_waitcnt lgkmcnt(4)
	v_mfma_f32_32x32x16_bf16 v[64:79], v[96:99], v[132:135], v[64:79]
	s_nop 0
	v_add_f32_e32 v204, v244, v204
	v_add_f32_e32 v205, v245, v205
	v_cvt_pk_bf16_f32 v214, v214, v215
	v_cvt_pk_bf16_f32 v215, v216, v217
	v_cvt_pk_bf16_f32 v216, v218, v219
	v_mfma_f32_32x32x16_bf16 v[80:95], v[104:107], v[132:135], v[80:95]
	v_cvt_pk_bf16_f32 v217, v220, v221
	v_cvt_pk_bf16_f32 v218, v222, v223
	v_cvt_pk_bf16_f32 v219, v224, v225
	v_cvt_pk_bf16_f32 v220, v226, v227
	v_cvt_pk_bf16_f32 v221, v228, v229
	v_mfma_f32_32x32x16_bf16 v[64:79], v[100:103], v[136:139], v[64:79]
	v_cvt_pk_bf16_f32 v222, v230, v231
	v_cvt_pk_bf16_f32 v223, v232, v233
	v_cvt_pk_bf16_f32 v224, v234, v235
	v_cvt_pk_bf16_f32 v225, v236, v237
	v_cvt_pk_bf16_f32 v226, v238, v239
	v_mfma_f32_32x32x16_bf16 v[80:95], v[108:111], v[136:139], v[80:95]
	v_cvt_pk_bf16_f32 v227, v240, v241
	v_cvt_pk_bf16_f32 v228, v242, v243
	v_cvt_pk_bf16_f32 v229, v244, v245
	v_add_f32_e32 v208, v204, v205
	v_add_f32_e32 v175, v175, v208
	s_branch .Lq_tailb1

; #define LAS __attribute__((address_space(3)))
; #define ATT_LSTORE(buf) do { LAS unsigned char* b_ = lds + (buf) * BUF; \
;         _Pragma("unroll") for (int i = 0; i < KPT; ++i) { if (KCH % NTHREADS == 0 || tid + i * NTHREADS < KCH) *(LAS u32x4*)(b_ + klo[i]) = kreg[i]; } \
;         _Pragma("unroll") for (int i = 0; i < VPT; ++i) *(LAS u32x4*)(b_ + vlo[i]) = vreg[i]; } while (0)
; template <int DQK, int DV, int FLAGS, int qp, int kp, int vts, int op> ...
;     ...
;             if (FLAGS & AF_ALIBI) { const float ab = -slope2 * (float)nrel - ((FLAGS & AF_ROBUST) ? 0.f : m);
; #pragma unroll
;                 for (int r = 0; r < 16; ++r) { const float c = (float)(16 * (r >> 3) + (r & 7)); p0[r] = __builtin_fmaf(slope2, c, ab); p1[r] = __builtin_fmaf(slope2, c + 32.f, ab); }
;     ...
;             for (int r = 0; r < 16; ++r) { p0[r] = __builtin_amdgcn_exp2f(p0[r]); p1[r] = __builtin_amdgcn_exp2f(p1[r]); }
; #pragma unroll
;             for (int r = 0; r < 16; r += 2) { rs2 += (f32x2){p0[r], p0[r + 1]}; rs2 += (f32x2){p1[r], p1[r + 1]}; }
;             l += rs2.x + rs2.y;
;             bf16x8 pf[4];
;             pf[0] = pack_bf16x8(p0, 0); pf[1] = pack_bf16x8(p0, 8); pf[2] = pack_bf16x8(p1, 0); pf[3] = pack_bf16x8(p1, 8);
;             __builtin_amdgcn_sched_barrier(0);
; #pragma unroll
;             for (int d = 0; d < NDB; ++d) {
;                 if (d + 1 < NDB) {
; #pragma unroll
;                     for (int ks = 0; ks < 4; ++ks) vf[(d + 1) & 1][ks] = *(const LAS bf16x8*)(vb + (d + 1) * 32 * VROW + ks * 32);
;                 }
; #pragma unroll
;                 for (int ks = 0; ks < 4; ++ks) o[d] = __builtin_amdgcn_mfma_f32_32x32x16_bf16(vf[d & 1][ks], pf[ks], o[d], 0, 0, 0);
;                 __builtin_amdgcn_sched_barrier(0);
;             }
;         }
;         if (skip && more) ATT_GLOAD((FLAGS & AF_REV) ? t - 1 : t + 1);
;         if (more) ATT_LSTORE(cur ^ 1);
.Ld_noqk0:
.Ld_top0:
	s_cmp_le_i32 s23, s24
	s_cbranch_scc1 .Ld_gen0
	s_add_i32 s13, s23, 1
	s_cmp_ge_i32 s13, s3
	s_cbranch_scc1 .Ld_gen0
	s_add_i32 s12, s23, -1
	s_and_b32 s12, s12, 3
	s_mulk_i32 s12, 0x6c00
	v_add3_u32 v245, s12, v203, v194
	ds_read_b128 v[224:227], v245 offset:13824
	ds_read_b128 v[228:231], v245 offset:13856
	ds_read_b128 v[232:235], v245 offset:13888
	ds_read_b128 v[236:239], v245 offset:13920
	s_add_i32 s12, s23, 1
	s_and_b32 s12, s12, 3
	s_mulk_i32 s12, 0x6c00
	v_add3_u32 v244, s12, v201, v194
	s_and_b32 s12, s23, 3
	s_mulk_i32 s12, 0x6c00
	v_add3_u32 v251, s12, v203, v194
	v_mfma_f32_32x32x16_bf16 v[64:79], v[160:163], v[112:115], v[64:79]
	v_exp_f32_e32 v80, v80
	v_exp_f32_e32 v81, v81
	v_exp_f32_e32 v96, v96
	v_exp_f32_e32 v97, v97
	v_add_u32_e32 v246, 64, v205
	v_mov_b32_e32 v240, v80
	v_mfma_f32_32x32x16_bf16 v[64:79], v[164:167], v[116:119], v[64:79]
	v_mov_b32_e32 v241, v81
	v_exp_f32_e32 v82, v82
	v_exp_f32_e32 v83, v83
	v_cvt_f32_i32_e32 v246, v246
	v_add_f32_e32 v240, v96, v240
	v_add_f32_e32 v241, v97, v241
	v_mfma_f32_32x32x16_bf16 v[64:79], v[168:171], v[120:123], v[64:79]
	v_exp_f32_e32 v98, v98
	v_exp_f32_e32 v99, v99
	v_fma_f32 v242, -v14, v246, -v222
	v_add_f32_e32 v240, v82, v240
	v_add_f32_e32 v241, v83, v241
	v_exp_f32_e32 v84, v84
	v_mfma_f32_32x32x16_bf16 v[64:79], v[172:175], v[124:127], v[64:79]
	v_exp_f32_e32 v85, v85
	v_fma_f32 v128, v14, s8, v242
	v_add_f32_e32 v240, v98, v240
	v_add_f32_e32 v241, v99, v241
	v_exp_f32_e32 v100, v100
	v_exp_f32_e32 v101, v101
	ds_read_b128 v[160:163], v245 offset:18432
	ds_read_b128 v[164:167], v245 offset:18464
	ds_read_b128 v[168:171], v245 offset:18496
	ds_read_b128 v[172:175], v245 offset:18528
	s_waitcnt lgkmcnt(4)
	v_mfma_f32_32x32x16_bf16 v[48:63], v[224:227], v[112:115], v[48:63]
	v_fma_f32 v129, v14, s9, v242
	v_add_f32_e32 v240, v84, v240
	v_add_f32_e32 v241, v85, v241
	v_exp_f32_e32 v86, v86
	v_exp_f32_e32 v87, v87
	v_fma_f32 v130, v14, s96, v242
	s_add_i32 s12, s23, 2
	s_and_b32 s13, s12, 3
	s_mulk_i32 s13, 0x6c00
	v_add_u32_e32 v248, s13, v204
	s_waitcnt vmcnt(0)
	ds_write_b128 v248, v[148:151]
	v_mfma_f32_32x32x16_bf16 v[48:63], v[228:231], v[116:119], v[48:63]
	v_add_f32_e32 v240, v100, v240
	v_add_f32_e32 v241, v101, v241
	v_exp_f32_e32 v102, v102
	v_exp_f32_e32 v103, v103
	v_fma_f32 v131, v14, s97, v242
	v_add_f32_e32 v240, v86, v240
	v_add_u32_e32 v249, s13, v200
	ds_write_b128 v249, v[152:155] offset:9216
	v_mfma_f32_32x32x16_bf16 v[48:63], v[232:235], v[120:123], v[48:63]
	v_add_f32_e32 v241, v87, v241
	v_exp_f32_e32 v88, v88
	v_exp_f32_e32 v89, v89
	v_fma_f32 v132, v14, s94, v242
	v_add_f32_e32 v240, v102, v240
	v_add_f32_e32 v241, v103, v241
	v_add_u32_e32 v250, s13, v202
	ds_write_b128 v250, v[156:159] offset:9216
	v_mfma_f32_32x32x16_bf16 v[48:63], v[236:239], v[124:127], v[48:63]
	v_exp_f32_e32 v104, v104
	v_exp_f32_e32 v105, v105
	v_fma_f32 v133, v14, s95, v242
	v_add_f32_e32 v240, v88, v240
	v_add_f32_e32 v241, v89, v241
	v_exp_f32_e32 v90, v90
	ds_read_b128 v[224:227], v245 offset:23040
	ds_read_b128 v[228:231], v245 offset:23072
	ds_read_b128 v[232:235], v245 offset:23104
	ds_read_b128 v[236:239], v245 offset:23136
	s_waitcnt lgkmcnt(4)
; #define LAS __attribute__((address_space(3)))
; template <int DQK, int DV, int FLAGS, int qp, int kp, int vts, int op> ...
;     ...
;             if (FLAGS & AF_ALIBI) { const float ab = -slope2 * (float)nrel - ((FLAGS & AF_ROBUST) ? 0.f : m);
; #pragma unroll
;                 for (int r = 0; r < 16; ++r) { const float c = (float)(16 * (r >> 3) + (r & 7)); p0[r] = __builtin_fmaf(slope2, c, ab); p1[r] = __builtin_fmaf(slope2, c + 32.f, ab); }
;             } else if (FLAGS & AF_ROBUST) {
; #pragma unroll
;                 for (int r = 0; r < 16; ++r) { p0[r] = 0.f; p1[r] = 0.f; }
;             } else { p0 = negm; p1 = negm; }
;             __builtin_amdgcn_sched_barrier(0);
; #pragma unroll
;             for (int c = 0; c < ND0 / 2; ++c) {
;                 if (c + 1 < ND0 / 2) {
; #pragma unroll
;                     for (int i = 0; i < 2; ++i) { kf[(c + 1) & 1][2 * i] = *(const LAS bf16x8*)(kb + (2 * c + 2 + i) * 32); kf[(c + 1) & 1][2 * i + 1] = *(const LAS bf16x8*)(kb + 32 * KROW + (2 * c + 2 + i) * 32); }
;                 }
; #pragma unroll
;                 for (int i = 0; i < 2; ++i) {
;                     p0 = __builtin_amdgcn_mfma_f32_32x32x16_bf16(kf[c & 1][2 * i], qr[2 * c + i], p0, 0, 0, 0);
;     ...
;             f32x2 rs2 = {0.f, 0.f};
; #pragma unroll
;             for (int r = 0; r < 16; ++r) { p0[r] = __builtin_amdgcn_exp2f(p0[r]); p1[r] = __builtin_amdgcn_exp2f(p1[r]); }
; #pragma unroll
;             for (int r = 0; r < 16; r += 2) { rs2 += (f32x2){p0[r], p0[r + 1]}; rs2 += (f32x2){p1[r], p1[r + 1]}; }
;             l += rs2.x + rs2.y;
;             bf16x8 pf[4];
;             pf[0] = pack_bf16x8(p0, 0); pf[1] = pack_bf16x8(p0, 8); pf[2] = pack_bf16x8(p1, 0); pf[3] = pack_bf16x8(p1, 8);
;             __builtin_amdgcn_sched_barrier(0);
; #pragma unroll
;             for (int d = 0; d < NDB; ++d) {
;                 if (d + 1 < NDB) {
; #pragma unroll
;                     for (int ks = 0; ks < 4; ++ks) vf[(d + 1) & 1][ks] = *(const LAS bf16x8*)(vb + (d + 1) * 32 * VROW + ks * 32);
;                 }
; #pragma unroll
;                 for (int ks = 0; ks < 4; ++ks) o[d] = __builtin_amdgcn_mfma_f32_32x32x16_bf16(vf[d & 1][ks], pf[ks], o[d], 0, 0, 0);
;                 __builtin_amdgcn_sched_barrier(0);
;             }
;         }
;         if (skip && more) ATT_GLOAD((FLAGS & AF_REV) ? t - 1 : t + 1);
;         if (more) ATT_LSTORE(cur ^ 1);
	v_mfma_f32_32x32x16_bf16 v[32:47], v[160:163], v[112:115], v[32:47]
	v_exp_f32_e32 v91, v91
	v_fma_f32 v134, v14, s92, v242
	v_add_f32_e32 v240, v104, v240
	v_add_f32_e32 v241, v105, v241
	v_exp_f32_e32 v106, v106
	v_exp_f32_e32 v107, v107
	v_mfma_f32_32x32x16_bf16 v[32:47], v[164:167], v[116:119], v[32:47]
	v_fma_f32 v135, v14, s93, v242
	v_add_f32_e32 v240, v90, v240
	v_add_f32_e32 v241, v91, v241
	v_exp_f32_e32 v92, v92
	v_exp_f32_e32 v93, v93
	v_fma_f32 v136, v14, s90, v242
	s_ashr_i32 s35, s34, 31
	s_lshl_b64 s[6:7], s[34:35], 17
	s_lshl_b64 s[10:11], s[34:35], 7
	s_add_u32 s10, s18, s10
	s_addc_u32 s11, s19, s11
	v_lshl_add_u64 v[246:247], v[206:207], 0, s[6:7]
	global_load_dwordx4 v[148:151], v[246:247], off
	v_mfma_f32_32x32x16_bf16 v[32:47], v[168:171], v[120:123], v[32:47]
	v_add_f32_e32 v240, v106, v240
	v_add_f32_e32 v241, v107, v241
	v_exp_f32_e32 v108, v108
	v_exp_f32_e32 v109, v109
	v_fma_f32 v137, v14, s91, v242
	v_add_f32_e32 v240, v92, v240
	v_lshl_add_u64 v[246:247], s[10:11], 0, v[0:1]
	global_load_dwordx4 v[152:155], v[246:247], off
	v_mfma_f32_32x32x16_bf16 v[32:47], v[172:175], v[124:127], v[32:47]
	v_add_f32_e32 v241, v93, v241
	v_exp_f32_e32 v94, v94
	v_exp_f32_e32 v95, v95
	v_fma_f32 v138, v14, s88, v242
	v_add_f32_e32 v240, v108, v240
	v_add_f32_e32 v241, v109, v241
	v_lshl_add_u64 v[246:247], s[10:11], 0, v[196:197]
	global_load_dwordx4 v[156:159], v[246:247], off
	s_add_i32 s34, s34, -1
	ds_read_b128 v[160:163], v244 offset:4608
	ds_read_b128 v[164:167], v244 offset:4640
	ds_read_b128 v[168:171], v244 offset:4672
	ds_read_b128 v[172:175], v244 offset:4704
	s_waitcnt lgkmcnt(4)
	v_mfma_f32_32x32x16_bf16 v[16:31], v[224:227], v[112:115], v[16:31]
	v_exp_f32_e32 v110, v110
	v_exp_f32_e32 v111, v111
	v_fma_f32 v139, v14, s89, v242
	v_add_f32_e32 v240, v94, v240
	v_add_f32_e32 v241, v95, v241
	v_fma_f32 v140, v14, s86, v242
	v_mfma_f32_32x32x16_bf16 v[16:31], v[228:231], v[116:119], v[16:31]
	v_fma_f32 v141, v14, s87, v242
	v_fma_f32 v142, v14, s78, v242
	v_fma_f32 v143, v14, s79, v242
	v_mfma_f32_32x32x16_bf16 v[16:31], v[232:235], v[120:123], v[16:31]
	v_mfma_f32_32x32x16_bf16 v[16:31], v[236:239], v[124:127], v[16:31]
	ds_read_b128 v[224:227], v244 offset:0
	ds_read_b128 v[228:231], v244 offset:32
	ds_read_b128 v[232:235], v244 offset:64
	ds_read_b128 v[236:239], v244 offset:96
	s_waitcnt lgkmcnt(4)
	v_mfma_f32_32x32x16_bf16 v[128:143], v[160:163], v[2:5], v[128:143]
	v_mov_b32_e32 v112, v242
	v_add_f32_e32 v113, v14, v242
	v_fma_f32 v114, v14, s62, v242
	v_fma_f32 v115, v14, s63, v242
	v_mfma_f32_32x32x16_bf16 v[128:143], v[164:167], v[6:9], v[128:143]
	v_fma_f32 v116, v14, s64, v242
	v_fma_f32 v117, v14, s65, v242
	v_fma_f32 v118, v14, s66, v242
	v_fma_f32 v119, v14, s67, v242
	v_mfma_f32_32x32x16_bf16 v[128:143], v[168:171], v[10:13], v[128:143]
	v_fma_f32 v120, v14, s68, v242
	v_fma_f32 v121, v14, s69, v242
	v_fma_f32 v122, v14, s70, v242
	v_fma_f32 v123, v14, s71, v242
	v_mfma_f32_32x32x16_bf16 v[128:143], v[172:175], v[144:147], v[128:143]
	v_fma_f32 v124, v14, s72, v242
	v_fma_f32 v125, v14, s73, v242
	v_fma_f32 v126, v14, s76, v242
	v_fma_f32 v127, v14, s77, v242
	ds_read_b128 v[160:163], v251 offset:9216
	ds_read_b128 v[164:167], v251 offset:9248
	ds_read_b128 v[168:171], v251 offset:9280
	ds_read_b128 v[172:175], v251 offset:9312
	s_waitcnt lgkmcnt(4)
	v_mfma_f32_32x32x16_bf16 v[112:127], v[224:227], v[2:5], v[112:127]
	s_nop 0
	v_add_f32_e32 v240, v110, v240
	v_add_f32_e32 v241, v111, v241
	v_cvt_pk_bf16_f32 v80, v80, v81
	v_cvt_pk_bf16_f32 v81, v82, v83
	v_cvt_pk_bf16_f32 v82, v84, v85
	v_mfma_f32_32x32x16_bf16 v[112:127], v[228:231], v[6:9], v[112:127]
	v_cvt_pk_bf16_f32 v83, v86, v87
	v_cvt_pk_bf16_f32 v84, v88, v89
	v_cvt_pk_bf16_f32 v85, v90, v91
	v_cvt_pk_bf16_f32 v86, v92, v93
	v_cvt_pk_bf16_f32 v87, v94, v95
	v_cvt_pk_bf16_f32 v88, v96, v97
	v_mfma_f32_32x32x16_bf16 v[112:127], v[232:235], v[10:13], v[112:127]
	v_cvt_pk_bf16_f32 v89, v98, v99
	v_cvt_pk_bf16_f32 v90, v100, v101
	v_cvt_pk_bf16_f32 v91, v102, v103
	v_cvt_pk_bf16_f32 v92, v104, v105
	v_cvt_pk_bf16_f32 v93, v106, v107
	v_cvt_pk_bf16_f32 v94, v108, v109
	v_mfma_f32_32x32x16_bf16 v[112:127], v[236:239], v[144:147], v[112:127]
	v_cvt_pk_bf16_f32 v95, v110, v111
	v_add_f32_e32 v247, v240, v241
	v_add_f32_e32 v199, v199, v247
	s_branch .Ld_tail0

; #define LAS __attribute__((address_space(3)))
; #define ATT_LSTORE(buf) do { LAS unsigned char* b_ = lds + (buf) * BUF; \
;         _Pragma("unroll") for (int i = 0; i < KPT; ++i) { if (KCH % NTHREADS == 0 || tid + i * NTHREADS < KCH) *(LAS u32x4*)(b_ + klo[i]) = kreg[i]; } \
;         _Pragma("unroll") for (int i = 0; i < VPT; ++i) *(LAS u32x4*)(b_ + vlo[i]) = vreg[i]; } while (0)
; template <int DQK, int DV, int FLAGS, int qp, int kp, int vts, int op> ...
;     ...
;             if (FLAGS & AF_ALIBI) { const float ab = -slope2 * (float)nrel - ((FLAGS & AF_ROBUST) ? 0.f : m);
; #pragma unroll
;                 for (int r = 0; r < 16; ++r) { const float c = (float)(16 * (r >> 3) + (r & 7)); p0[r] = __builtin_fmaf(slope2, c, ab); p1[r] = __builtin_fmaf(slope2, c + 32.f, ab); }
;     ...
;             for (int r = 0; r < 16; ++r) { p0[r] = __builtin_amdgcn_exp2f(p0[r]); p1[r] = __builtin_amdgcn_exp2f(p1[r]); }
; #pragma unroll
;             for (int r = 0; r < 16; r += 2) { rs2 += (f32x2){p0[r], p0[r + 1]}; rs2 += (f32x2){p1[r], p1[r + 1]}; }
;             l += rs2.x + rs2.y;
;             bf16x8 pf[4];
;             pf[0] = pack_bf16x8(p0, 0); pf[1] = pack_bf16x8(p0, 8); pf[2] = pack_bf16x8(p1, 0); pf[3] = pack_bf16x8(p1, 8);
;             __builtin_amdgcn_sched_barrier(0);
; #pragma unroll
;             for (int d = 0; d < NDB; ++d) {
;                 if (d + 1 < NDB) {
; #pragma unroll
;                     for (int ks = 0; ks < 4; ++ks) vf[(d + 1) & 1][ks] = *(const LAS bf16x8*)(vb + (d + 1) * 32 * VROW + ks * 32);
;                 }
; #pragma unroll
;                 for (int ks = 0; ks < 4; ++ks) o[d] = __builtin_amdgcn_mfma_f32_32x32x16_bf16(vf[d & 1][ks], pf[ks], o[d], 0, 0, 0);
;                 __builtin_amdgcn_sched_barrier(0);
;             }
;         }
;         if (skip && more) ATT_GLOAD((FLAGS & AF_REV) ? t - 1 : t + 1);
;         if (more) ATT_LSTORE(cur ^ 1);
.Ld_top1:
	s_cmp_le_i32 s23, s24
	s_cbranch_scc1 .Ld_gen1
	s_add_i32 s13, s23, 1
	s_cmp_ge_i32 s13, s3
	s_cbranch_scc1 .Ld_gen1
	s_add_i32 s12, s23, -1
	s_and_b32 s12, s12, 3
	s_mulk_i32 s12, 0x6c00
	v_add3_u32 v245, s12, v203, v194
	ds_read_b128 v[224:227], v245 offset:13824
	ds_read_b128 v[228:231], v245 offset:13856
	ds_read_b128 v[232:235], v245 offset:13888
	ds_read_b128 v[236:239], v245 offset:13920
	s_add_i32 s12, s23, 1
	s_and_b32 s12, s12, 3
	s_mulk_i32 s12, 0x6c00
	v_add3_u32 v244, s12, v201, v194
	s_and_b32 s12, s23, 3
	s_mulk_i32 s12, 0x6c00
	v_add3_u32 v251, s12, v203, v194
	v_mfma_f32_32x32x16_bf16 v[64:79], v[160:163], v[80:83], v[64:79]
	v_exp_f32_e32 v112, v112
	v_exp_f32_e32 v113, v113
	v_exp_f32_e32 v128, v128
	v_exp_f32_e32 v129, v129
	v_add_u32_e32 v246, 64, v205
	v_mov_b32_e32 v240, v112
	v_mfma_f32_32x32x16_bf16 v[64:79], v[164:167], v[84:87], v[64:79]
	v_mov_b32_e32 v241, v113
	v_exp_f32_e32 v114, v114
	v_exp_f32_e32 v115, v115
	v_cvt_f32_i32_e32 v246, v246
	v_add_f32_e32 v240, v128, v240
	v_add_f32_e32 v241, v129, v241
	v_mfma_f32_32x32x16_bf16 v[64:79], v[168:171], v[88:91], v[64:79]
	v_exp_f32_e32 v130, v130
	v_exp_f32_e32 v131, v131
	v_fma_f32 v242, -v14, v246, -v222
	v_add_f32_e32 v240, v114, v240
	v_add_f32_e32 v241, v115, v241
	v_exp_f32_e32 v116, v116
	v_mfma_f32_32x32x16_bf16 v[64:79], v[172:175], v[92:95], v[64:79]
	v_exp_f32_e32 v117, v117
	v_fma_f32 v96, v14, s8, v242
	v_add_f32_e32 v240, v130, v240
	v_add_f32_e32 v241, v131, v241
	v_exp_f32_e32 v132, v132
	v_exp_f32_e32 v133, v133
	ds_read_b128 v[160:163], v245 offset:18432
	ds_read_b128 v[164:167], v245 offset:18464
	ds_read_b128 v[168:171], v245 offset:18496
	ds_read_b128 v[172:175], v245 offset:18528
	s_waitcnt lgkmcnt(4)
	v_mfma_f32_32x32x16_bf16 v[48:63], v[224:227], v[80:83], v[48:63]
	v_fma_f32 v97, v14, s9, v242
	v_add_f32_e32 v240, v116, v240
	v_add_f32_e32 v241, v117, v241
	v_exp_f32_e32 v118, v118
	v_exp_f32_e32 v119, v119
	v_fma_f32 v98, v14, s96, v242
	s_add_i32 s12, s23, 2
	s_and_b32 s13, s12, 3
	s_mulk_i32 s13, 0x6c00
	v_add_u32_e32 v248, s13, v204
	s_waitcnt vmcnt(0)
	ds_write_b128 v248, v[148:151]
	v_mfma_f32_32x32x16_bf16 v[48:63], v[228:231], v[84:87], v[48:63]
	v_add_f32_e32 v240, v132, v240
	v_add_f32_e32 v241, v133, v241
	v_exp_f32_e32 v134, v134
	v_exp_f32_e32 v135, v135
	v_fma_f32 v99, v14, s97, v242
	v_add_f32_e32 v240, v118, v240
	v_add_u32_e32 v249, s13, v200
	ds_write_b128 v249, v[152:155] offset:9216
	v_mfma_f32_32x32x16_bf16 v[48:63], v[232:235], v[88:91], v[48:63]
	v_add_f32_e32 v241, v119, v241
	v_exp_f32_e32 v120, v120
	v_exp_f32_e32 v121, v121
	v_fma_f32 v100, v14, s94, v242
	v_add_f32_e32 v240, v134, v240
	v_add_f32_e32 v241, v135, v241
	v_add_u32_e32 v250, s13, v202
	ds_write_b128 v250, v[156:159] offset:9216
	v_mfma_f32_32x32x16_bf16 v[48:63], v[236:239], v[92:95], v[48:63]
	v_exp_f32_e32 v136, v136
	v_exp_f32_e32 v137, v137
	v_fma_f32 v101, v14, s95, v242
	v_add_f32_e32 v240, v120, v240
	v_add_f32_e32 v241, v121, v241
	v_exp_f32_e32 v122, v122
	ds_read_b128 v[224:227], v245 offset:23040
	ds_read_b128 v[228:231], v245 offset:23072
	ds_read_b128 v[232:235], v245 offset:23104
	ds_read_b128 v[236:239], v245 offset:23136
	s_waitcnt lgkmcnt(4)
; #define LAS __attribute__((address_space(3)))
; template <int DQK, int DV, int FLAGS, int qp, int kp, int vts, int op> ...
;     ...
;             if (FLAGS & AF_ALIBI) { const float ab = -slope2 * (float)nrel - ((FLAGS & AF_ROBUST) ? 0.f : m);
; #pragma unroll
;                 for (int r = 0; r < 16; ++r) { const float c = (float)(16 * (r >> 3) + (r & 7)); p0[r] = __builtin_fmaf(slope2, c, ab); p1[r] = __builtin_fmaf(slope2, c + 32.f, ab); }
;             } else if (FLAGS & AF_ROBUST) {
; #pragma unroll
;                 for (int r = 0; r < 16; ++r) { p0[r] = 0.f; p1[r] = 0.f; }
;             } else { p0 = negm; p1 = negm; }
;             __builtin_amdgcn_sched_barrier(0);
; #pragma unroll
;             for (int c = 0; c < ND0 / 2; ++c) {
;                 if (c + 1 < ND0 / 2) {
; #pragma unroll
;                     for (int i = 0; i < 2; ++i) { kf[(c + 1) & 1][2 * i] = *(const LAS bf16x8*)(kb + (2 * c + 2 + i) * 32); kf[(c + 1) & 1][2 * i + 1] = *(const LAS bf16x8*)(kb + 32 * KROW + (2 * c + 2 + i) * 32); }
;                 }
; #pragma unroll
;                 for (int i = 0; i < 2; ++i) {
;                     p0 = __builtin_amdgcn_mfma_f32_32x32x16_bf16(kf[c & 1][2 * i], qr[2 * c + i], p0, 0, 0, 0);
;     ...
;             f32x2 rs2 = {0.f, 0.f};
; #pragma unroll
;             for (int r = 0; r < 16; ++r) { p0[r] = __builtin_amdgcn_exp2f(p0[r]); p1[r] = __builtin_amdgcn_exp2f(p1[r]); }
; #pragma unroll
;             for (int r = 0; r < 16; r += 2) { rs2 += (f32x2){p0[r], p0[r + 1]}; rs2 += (f32x2){p1[r], p1[r + 1]}; }
;             l += rs2.x + rs2.y;
;             bf16x8 pf[4];
;             pf[0] = pack_bf16x8(p0, 0); pf[1] = pack_bf16x8(p0, 8); pf[2] = pack_bf16x8(p1, 0); pf[3] = pack_bf16x8(p1, 8);
;             __builtin_amdgcn_sched_barrier(0);
; #pragma unroll
;             for (int d = 0; d < NDB; ++d) {
;                 if (d + 1 < NDB) {
; #pragma unroll
;                     for (int ks = 0; ks < 4; ++ks) vf[(d + 1) & 1][ks] = *(const LAS bf16x8*)(vb + (d + 1) * 32 * VROW + ks * 32);
;                 }
; #pragma unroll
;                 for (int ks = 0; ks < 4; ++ks) o[d] = __builtin_amdgcn_mfma_f32_32x32x16_bf16(vf[d & 1][ks], pf[ks], o[d], 0, 0, 0);
;                 __builtin_amdgcn_sched_barrier(0);
;             }
;         }
;         if (skip && more) ATT_GLOAD((FLAGS & AF_REV) ? t - 1 : t + 1);
;         if (more) ATT_LSTORE(cur ^ 1);
	v_mfma_f32_32x32x16_bf16 v[32:47], v[160:163], v[80:83], v[32:47]
	v_exp_f32_e32 v123, v123
	v_fma_f32 v102, v14, s92, v242
	v_add_f32_e32 v240, v136, v240
	v_add_f32_e32 v241, v137, v241
	v_exp_f32_e32 v138, v138
	v_exp_f32_e32 v139, v139
	v_mfma_f32_32x32x16_bf16 v[32:47], v[164:167], v[84:87], v[32:47]
	v_fma_f32 v103, v14, s93, v242
	v_add_f32_e32 v240, v122, v240
	v_add_f32_e32 v241, v123, v241
	v_exp_f32_e32 v124, v124
	v_exp_f32_e32 v125, v125
	v_fma_f32 v104, v14, s90, v242
	s_ashr_i32 s35, s34, 31
	s_lshl_b64 s[6:7], s[34:35], 17
	s_lshl_b64 s[10:11], s[34:35], 7
	s_add_u32 s10, s18, s10
	s_addc_u32 s11, s19, s11
	v_lshl_add_u64 v[246:247], v[206:207], 0, s[6:7]
	global_load_dwordx4 v[148:151], v[246:247], off
	v_mfma_f32_32x32x16_bf16 v[32:47], v[168:171], v[88:91], v[32:47]
	v_add_f32_e32 v240, v138, v240
	v_add_f32_e32 v241, v139, v241
	v_exp_f32_e32 v140, v140
	v_exp_f32_e32 v141, v141
	v_fma_f32 v105, v14, s91, v242
	v_add_f32_e32 v240, v124, v240
	v_lshl_add_u64 v[246:247], s[10:11], 0, v[0:1]
	global_load_dwordx4 v[152:155], v[246:247], off
	v_mfma_f32_32x32x16_bf16 v[32:47], v[172:175], v[92:95], v[32:47]
	v_add_f32_e32 v241, v125, v241
	v_exp_f32_e32 v126, v126
	v_exp_f32_e32 v127, v127
	v_fma_f32 v106, v14, s88, v242
	v_add_f32_e32 v240, v140, v240
	v_add_f32_e32 v241, v141, v241
	v_lshl_add_u64 v[246:247], s[10:11], 0, v[196:197]
	global_load_dwordx4 v[156:159], v[246:247], off
	s_add_i32 s34, s34, -1
	ds_read_b128 v[160:163], v244 offset:4608
	ds_read_b128 v[164:167], v244 offset:4640
	ds_read_b128 v[168:171], v244 offset:4672
	ds_read_b128 v[172:175], v244 offset:4704
	s_waitcnt lgkmcnt(4)
	v_mfma_f32_32x32x16_bf16 v[16:31], v[224:227], v[80:83], v[16:31]
	v_exp_f32_e32 v142, v142
	v_exp_f32_e32 v143, v143
	v_fma_f32 v107, v14, s89, v242
	v_add_f32_e32 v240, v126, v240
	v_add_f32_e32 v241, v127, v241
	v_fma_f32 v108, v14, s86, v242
	v_mfma_f32_32x32x16_bf16 v[16:31], v[228:231], v[84:87], v[16:31]
	v_fma_f32 v109, v14, s87, v242
	v_fma_f32 v110, v14, s78, v242
	v_fma_f32 v111, v14, s79, v242
	v_mfma_f32_32x32x16_bf16 v[16:31], v[232:235], v[88:91], v[16:31]
	v_mfma_f32_32x32x16_bf16 v[16:31], v[236:239], v[92:95], v[16:31]
	ds_read_b128 v[224:227], v244 offset:0
	ds_read_b128 v[228:231], v244 offset:32
	ds_read_b128 v[232:235], v244 offset:64
	ds_read_b128 v[236:239], v244 offset:96
	s_waitcnt lgkmcnt(4)
	v_mfma_f32_32x32x16_bf16 v[96:111], v[160:163], v[2:5], v[96:111]
	v_mov_b32_e32 v80, v242
	v_add_f32_e32 v81, v14, v242
	v_fma_f32 v82, v14, s62, v242
	v_fma_f32 v83, v14, s63, v242
	v_mfma_f32_32x32x16_bf16 v[96:111], v[164:167], v[6:9], v[96:111]
	v_fma_f32 v84, v14, s64, v242
	v_fma_f32 v85, v14, s65, v242
	v_fma_f32 v86, v14, s66, v242
	v_fma_f32 v87, v14, s67, v242
	v_mfma_f32_32x32x16_bf16 v[96:111], v[168:171], v[10:13], v[96:111]
	v_fma_f32 v88, v14, s68, v242
	v_fma_f32 v89, v14, s69, v242
	v_fma_f32 v90, v14, s70, v242
	v_fma_f32 v91, v14, s71, v242
	v_mfma_f32_32x32x16_bf16 v[96:111], v[172:175], v[144:147], v[96:111]
	v_fma_f32 v92, v14, s72, v242
	v_fma_f32 v93, v14, s73, v242
	v_fma_f32 v94, v14, s76, v242
	v_fma_f32 v95, v14, s77, v242
	ds_read_b128 v[160:163], v251 offset:9216
	ds_read_b128 v[164:167], v251 offset:9248
	ds_read_b128 v[168:171], v251 offset:9280
	ds_read_b128 v[172:175], v251 offset:9312
	s_waitcnt lgkmcnt(4)
	v_mfma_f32_32x32x16_bf16 v[80:95], v[224:227], v[2:5], v[80:95]
	s_nop 0
	v_add_f32_e32 v240, v142, v240
	v_add_f32_e32 v241, v143, v241
	v_cvt_pk_bf16_f32 v112, v112, v113
	v_cvt_pk_bf16_f32 v113, v114, v115
	v_cvt_pk_bf16_f32 v114, v116, v117
	v_mfma_f32_32x32x16_bf16 v[80:95], v[228:231], v[6:9], v[80:95]
	v_cvt_pk_bf16_f32 v115, v118, v119
	v_cvt_pk_bf16_f32 v116, v120, v121
	v_cvt_pk_bf16_f32 v117, v122, v123
	v_cvt_pk_bf16_f32 v118, v124, v125
	v_cvt_pk_bf16_f32 v119, v126, v127
	v_cvt_pk_bf16_f32 v120, v128, v129
	v_mfma_f32_32x32x16_bf16 v[80:95], v[232:235], v[10:13], v[80:95]
	v_cvt_pk_bf16_f32 v121, v130, v131
	v_cvt_pk_bf16_f32 v122, v132, v133
	v_cvt_pk_bf16_f32 v123, v134, v135
	v_cvt_pk_bf16_f32 v124, v136, v137
	v_cvt_pk_bf16_f32 v125, v138, v139
	v_cvt_pk_bf16_f32 v126, v140, v141
	v_mfma_f32_32x32x16_bf16 v[80:95], v[236:239], v[144:147], v[80:95]
	v_cvt_pk_bf16_f32 v127, v142, v143
	v_add_f32_e32 v247, v240, v241
	v_add_f32_e32 v199, v199, v247
	s_branch .Ld_tail1

; #define UNPK8(v, f) do { f[0] = bflo(v.x); f[1] = bfhi(v.x); f[2] = bflo(v.y); f[3] = bfhi(v.y); f[4] = bflo(v.z); f[5] = bfhi(v.z); f[6] = bflo(v.w); f[7] = bfhi(v.w); } while (0)
; #define PACK8(v, f) do { v.x = pk2(f[0], f[1]); v.y = pk2(f[2], f[3]); v.z = pk2(f[4], f[5]); v.w = pk2(f[6], f[7]); } while (0)
; __device__ __forceinline__ float shfl_xor_l(float v, int o, int lane) { return __builtin_bit_cast(float, __builtin_amdgcn_ds_bpermute((lane ^ o) << 2, __builtin_bit_cast(int, v))); }
; #define INP(i) (*(const float* const volatile __attribute__((address_space(4)))*)((const __attribute__((address_space(4))) char*)__builtin_amdgcn_kernarg_segment_ptr() + 8 * (i)))
; #define REP(k) for (int rep_ = 0; rep_ < 1 + (int)((DUPMASK >> (k)) & 1u); ++rep_)
; __global__ void __launch_bounds__(NTHREADS, 2) mega_fwd(Args args) {
;     ...
;             REP(18) if (IN(18)) {
;                 PHASE_IDS;
;                 const float lam = *(const float*)(ws + S_LAM); const float osc = 1.0f - (0.8f - 0.6f * expf(-0.3f));
;                 const float* gsub = INP(19);
;                 for (int it = gw; it < T * 2; it += NGW) {
;                     const size_t off = (size_t)it * 512 + lane * 8;
;                     const u32x4 v1 = *(const u32x4*)((const bf16*)(ws + A_O1) + off), v2 = *(const u32x4*)((const bf16*)(ws + A_O2) + off);
;                     float a[8], b2[8]; UNPK8(v1, a); UNPK8(v2, b2);
;                     float ss = 0.f;
; #pragma unroll
;                     for (int i = 0; i < 8; ++i) { a[i] -= lam * b2[i]; ss += a[i] * a[i]; }
;                     ss += shfl_xor_l(ss, 1, lane); ss += shfl_xor_l(ss, 2, lane); ss += shfl_xor_l(ss, 4, lane); ss += shfl_xor_l(ss, 8, lane);
;                     const float r = (1.0f / sqrtf(ss * (1.f / 128.f) + EPS)) * osc;
;                     const float* g = gsub + (lane & 15) * 8;
; #pragma unroll
;                     for (int i = 0; i < 8; ++i) a[i] *= r * g[i];
;                     u32x4 w; PACK8(w, a); *(u32x4*)((bf16*)(ws + A_DO) + off) = w;
;                 }
.LBB0_1013:
	v_readlane_b32 s2, v254, 20
	v_readlane_b32 s3, v254, 21
	s_andn2_b64 vcc, exec, s[2:3]
	s_cbranch_vccnz .LBB0_1017
	v_mov_b32_e32 v0, v212
	s_load_dwordx2 s[6:7], s[82:83], 0x98
	v_readfirstlane_b32 s2, v0
	s_ashr_i32 s3, s2, 6
	v_readlane_b32 s2, v255, 31
	s_add_i32 s2, s3, s2
	s_cmp_gt_i32 s2, 0xffff
	s_cbranch_scc1 .LBB0_1017
	v_readlane_b32 s4, v252, 20
	v_readlane_b32 s5, v252, 21
	v_and_b32_e32 v6, 63, v0
	v_lshlrev_b32_e32 v0, 5, v0
	v_and_b32_e32 v0, 0x1e0, v0
	v_lshlrev_b32_e32 v3, 2, v6
	s_waitcnt lgkmcnt(0)
	v_lshl_add_u64 v[4:5], s[6:7], 0, v[0:1]
	global_load_dword v2, v1, s[4:5]
	v_readlane_b32 s4, v252, 18
	v_readlane_b32 s5, v252, 19
	s_load_dword s4, s[4:5], 0x0
	s_ashr_i32 s5, s3, 31
	v_lshlrev_b32_e32 v0, 4, v6
	v_xor_b32_e32 v8, 4, v3
	v_xor_b32_e32 v9, 8, v3
	s_waitcnt lgkmcnt(0)
	s_lshl_b32 s8, s4, 3
	v_readlane_b32 s4, v255, 31
	s_add_u32 s4, s4, s3
	v_readlane_b32 s3, v255, 32
	s_addc_u32 s5, s3, s5
	s_lshl_b64 s[4:5], s[4:5], 10
	s_add_u32 s4, s74, s4
	s_addc_u32 s5, s75, s5
	s_ashr_i32 s9, s8, 31
	s_waitcnt vmcnt(0)
	v_xor_b32_e32 v10, 16, v3
	v_xor_b32_e32 v11, 32, v3
	v_lshl_add_u64 v[6:7], s[4:5], 0, v[0:1]
	s_lshl_b64 s[10:11], s[8:9], 10
	v_mov_b32_e32 v3, v2
	global_load_dwordx4 v[24:27], v[4:5], off
	global_load_dwordx4 v[20:23], v[4:5], off offset:16
	v_mov_b32_e32 v86, 1.5
	v_mov_b32_e32 v44, v6
	v_mov_b32_e32 v45, v7
	global_load_dwordx4 v[28:31], v[44:45], off
	v_add_co_u32_e32 v82, vcc, 0x4000000, v44
	s_nop 1
	v_addc_co_u32_e32 v83, vcc, 0, v45, vcc
	global_load_dwordx4 v[32:35], v[82:83], off
	s_waitcnt vmcnt(0)
.Lp18_it0:
	s_add_i32 s2, s2, s8
	s_cmp_lt_i32 s2, 0x10000
	s_cbranch_scc0 .Lp18_last0
	v_lshl_add_u64 v[46:47], v[44:45], 0, s[10:11]
	global_load_dwordx4 v[36:39], v[46:47], off
	v_add_co_u32_e32 v82, vcc, 0x4000000, v46
	s_nop 1
	v_addc_co_u32_e32 v83, vcc, 0, v47, vcc
	global_load_dwordx4 v[40:43], v[82:83], off
	v_lshlrev_b32_e32 v48, 16, v28
	v_and_b32_e32 v49, 0xffff0000, v28
	v_lshlrev_b32_e32 v56, 16, v32
	v_and_b32_e32 v57, 0xffff0000, v32
	v_lshlrev_b32_e32 v50, 16, v29
	v_and_b32_e32 v51, 0xffff0000, v29
	v_lshlrev_b32_e32 v58, 16, v33
	v_and_b32_e32 v59, 0xffff0000, v33
	v_lshlrev_b32_e32 v52, 16, v30
	v_and_b32_e32 v53, 0xffff0000, v30
	v_lshlrev_b32_e32 v60, 16, v34
	v_and_b32_e32 v61, 0xffff0000, v34
	v_lshlrev_b32_e32 v54, 16, v31
	v_and_b32_e32 v55, 0xffff0000, v31
	v_lshlrev_b32_e32 v62, 16, v35
	v_and_b32_e32 v63, 0xffff0000, v35
	v_fma_f32 v48, -v2, v56, v48
	v_fma_f32 v49, -v2, v57, v49
	v_fma_f32 v50, -v2, v58, v50
	v_fma_f32 v51, -v2, v59, v51
	v_fma_f32 v52, -v2, v60, v52
	v_fma_f32 v53, -v2, v61, v53
	v_fma_f32 v54, -v2, v62, v54
	v_fma_f32 v55, -v2, v63, v55
	v_mul_f32_e32 v64, v48, v48
	v_fmac_f32_e32 v64, v49, v49
	v_fmac_f32_e32 v64, v50, v50
	v_fmac_f32_e32 v64, v51, v51
	v_fmac_f32_e32 v64, v52, v52
	v_fmac_f32_e32 v64, v53, v53
	v_fmac_f32_e32 v64, v54, v54
	v_fmac_f32_e32 v64, v55, v55
	s_nop 1
	v_add_f32_dpp v65, v64, v64 quad_perm:[1,0,3,2] row_mask:0xf bank_mask:0xf
	s_nop 1
	v_add_f32_dpp v64, v65, v65 quad_perm:[2,3,0,1] row_mask:0xf bank_mask:0xf
	s_nop 1
	v_add_f32_dpp v65, v64, v64 row_half_mirror row_mask:0xf bank_mask:0xf
	s_nop 1
	v_add_f32_dpp v64, v65, v65 row_mirror row_mask:0xf bank_mask:0xf
	v_fmamk_f32 v65, v64, 0x3c000000, v214
	v_rsq_f32_e32 v66, v65
	s_nop 0
	v_mul_f32_e32 v67, v65, v66
	v_mul_f32_e32 v67, v67, v66
	v_fma_f32 v67, v67, -0.5, v86
	v_mul_f32_e32 v66, v66, v67
	v_mul_f32_e32 v66, 0x3f24fd5c, v66
	v_mul_f32_e32 v68, v66, v24
	v_mul_f32_e32 v69, v66, v25
	v_mul_f32_e32 v70, v66, v26
	v_mul_f32_e32 v71, v66, v27
	v_mul_f32_e32 v72, v66, v20
	v_mul_f32_e32 v73, v66, v21
	v_mul_f32_e32 v74, v66, v22
	v_mul_f32_e32 v75, v66, v23
	v_mul_f32_e32 v48, v48, v68
	v_mul_f32_e32 v49, v49, v69
	v_mul_f32_e32 v50, v50, v70
	v_mul_f32_e32 v51, v51, v71
	v_mul_f32_e32 v52, v52, v72
	v_mul_f32_e32 v53, v53, v73
	v_mul_f32_e32 v54, v54, v74
	v_mul_f32_e32 v55, v55, v75
	v_cvt_pk_bf16_f32 v76, v48, v49
	v_cvt_pk_bf16_f32 v77, v50, v51
	v_cvt_pk_bf16_f32 v78, v52, v53
	v_cvt_pk_bf16_f32 v79, v54, v55
	v_add_co_u32_e32 v84, vcc, 0x8000000, v44
	s_nop 1
	v_addc_co_u32_e32 v85, vcc, 0, v45, vcc
	global_store_dwordx4 v[84:85], v[76:79], off
	s_waitcnt vmcnt(1)
.Lp18_it1:
	s_add_i32 s2, s2, s8
	s_cmp_lt_i32 s2, 0x10000
	s_cbranch_scc0 .Lp18_last1
	v_lshl_add_u64 v[44:45], v[46:47], 0, s[10:11]
	global_load_dwordx4 v[28:31], v[44:45], off
	v_add_co_u32_e32 v82, vcc, 0x4000000, v44
	s_nop 1
	v_addc_co_u32_e32 v83, vcc, 0, v45, vcc
	global_load_dwordx4 v[32:35], v[82:83], off
	v_lshlrev_b32_e32 v48, 16, v36
	v_and_b32_e32 v49, 0xffff0000, v36
	v_lshlrev_b32_e32 v56, 16, v40
	v_and_b32_e32 v57, 0xffff0000, v40
	v_lshlrev_b32_e32 v50, 16, v37
	v_and_b32_e32 v51, 0xffff0000, v37
	v_lshlrev_b32_e32 v58, 16, v41
	v_and_b32_e32 v59, 0xffff0000, v41
	v_lshlrev_b32_e32 v52, 16, v38
	v_and_b32_e32 v53, 0xffff0000, v38
	v_lshlrev_b32_e32 v60, 16, v42
	v_and_b32_e32 v61, 0xffff0000, v42
	v_lshlrev_b32_e32 v54, 16, v39
	v_and_b32_e32 v55, 0xffff0000, v39
	v_lshlrev_b32_e32 v62, 16, v43
	v_and_b32_e32 v63, 0xffff0000, v43
	v_fma_f32 v48, -v2, v56, v48
	v_fma_f32 v49, -v2, v57, v49
	v_fma_f32 v50, -v2, v58, v50
	v_fma_f32 v51, -v2, v59, v51
	v_fma_f32 v52, -v2, v60, v52
	v_fma_f32 v53, -v2, v61, v53
	v_fma_f32 v54, -v2, v62, v54
	v_fma_f32 v55, -v2, v63, v55
	v_mul_f32_e32 v64, v48, v48
	v_fmac_f32_e32 v64, v49, v49
	v_fmac_f32_e32 v64, v50, v50
	v_fmac_f32_e32 v64, v51, v51
	v_fmac_f32_e32 v64, v52, v52
	v_fmac_f32_e32 v64, v53, v53
	v_fmac_f32_e32 v64, v54, v54
	v_fmac_f32_e32 v64, v55, v55
	s_nop 1
	v_add_f32_dpp v65, v64, v64 quad_perm:[1,0,3,2] row_mask:0xf bank_mask:0xf
	s_nop 1
	v_add_f32_dpp v64, v65, v65 quad_perm:[2,3,0,1] row_mask:0xf bank_mask:0xf
	s_nop 1
	v_add_f32_dpp v65, v64, v64 row_half_mirror row_mask:0xf bank_mask:0xf
	s_nop 1
	v_add_f32_dpp v64, v65, v65 row_mirror row_mask:0xf bank_mask:0xf
	v_fmamk_f32 v65, v64, 0x3c000000, v214
	v_rsq_f32_e32 v66, v65
	s_nop 0
	v_mul_f32_e32 v67, v65, v66
	v_mul_f32_e32 v67, v67, v66
	v_fma_f32 v67, v67, -0.5, v86
	v_mul_f32_e32 v66, v66, v67
	v_mul_f32_e32 v66, 0x3f24fd5c, v66
	v_mul_f32_e32 v68, v66, v24
	v_mul_f32_e32 v69, v66, v25
	v_mul_f32_e32 v70, v66, v26
	v_mul_f32_e32 v71, v66, v27
	v_mul_f32_e32 v72, v66, v20
	v_mul_f32_e32 v73, v66, v21
	v_mul_f32_e32 v74, v66, v22
	v_mul_f32_e32 v75, v66, v23
	v_mul_f32_e32 v48, v48, v68
	v_mul_f32_e32 v49, v49, v69
	v_mul_f32_e32 v50, v50, v70
	v_mul_f32_e32 v51, v51, v71
	v_mul_f32_e32 v52, v52, v72
	v_mul_f32_e32 v53, v53, v73
	v_mul_f32_e32 v54, v54, v74
	v_mul_f32_e32 v55, v55, v75
	v_cvt_pk_bf16_f32 v76, v48, v49
	v_cvt_pk_bf16_f32 v77, v50, v51
	v_cvt_pk_bf16_f32 v78, v52, v53
	v_cvt_pk_bf16_f32 v79, v54, v55
	v_add_co_u32_e32 v84, vcc, 0x8000000, v46
	s_nop 1
	v_addc_co_u32_e32 v85, vcc, 0, v47, vcc
	global_store_dwordx4 v[84:85], v[76:79], off
	s_waitcnt vmcnt(1)
	s_branch .Lp18_it0
; #define UNPK8(v, f) do { f[0] = bflo(v.x); f[1] = bfhi(v.x); f[2] = bflo(v.y); f[3] = bfhi(v.y); f[4] = bflo(v.z); f[5] = bfhi(v.z); f[6] = bflo(v.w); f[7] = bfhi(v.w); } while (0)
; #define PACK8(v, f) do { v.x = pk2(f[0], f[1]); v.y = pk2(f[2], f[3]); v.z = pk2(f[4], f[5]); v.w = pk2(f[6], f[7]); } while (0)
; __device__ __forceinline__ float shfl_xor_l(float v, int o, int lane) { return __builtin_bit_cast(float, __builtin_amdgcn_ds_bpermute((lane ^ o) << 2, __builtin_bit_cast(int, v))); }
; __global__ void __launch_bounds__(NTHREADS, 2) mega_fwd(Args args) {
;     ...
;                 for (int it = gw; it < T * 2; it += NGW) {
;                     const size_t off = (size_t)it * 512 + lane * 8;
;                     const u32x4 v1 = *(const u32x4*)((const bf16*)(ws + A_O1) + off), v2 = *(const u32x4*)((const bf16*)(ws + A_O2) + off);
;                     float a[8], b2[8]; UNPK8(v1, a); UNPK8(v2, b2);
;                     float ss = 0.f;
; #pragma unroll
;                     for (int i = 0; i < 8; ++i) { a[i] -= lam * b2[i]; ss += a[i] * a[i]; }
;                     ss += shfl_xor_l(ss, 1, lane); ss += shfl_xor_l(ss, 2, lane); ss += shfl_xor_l(ss, 4, lane); ss += shfl_xor_l(ss, 8, lane);
;                     const float r = (1.0f / sqrtf(ss * (1.f / 128.f) + EPS)) * osc;
;                     const float* g = gsub + (lane & 15) * 8;
; #pragma unroll
;                     for (int i = 0; i < 8; ++i) a[i] *= r * g[i];
;                     u32x4 w; PACK8(w, a); *(u32x4*)((bf16*)(ws + A_DO) + off) = w;
.Lp18_last0:
	v_lshlrev_b32_e32 v48, 16, v28
	v_and_b32_e32 v49, 0xffff0000, v28
	v_lshlrev_b32_e32 v56, 16, v32
	v_and_b32_e32 v57, 0xffff0000, v32
	v_lshlrev_b32_e32 v50, 16, v29
	v_and_b32_e32 v51, 0xffff0000, v29
	v_lshlrev_b32_e32 v58, 16, v33
	v_and_b32_e32 v59, 0xffff0000, v33
	v_lshlrev_b32_e32 v52, 16, v30
	v_and_b32_e32 v53, 0xffff0000, v30
	v_lshlrev_b32_e32 v60, 16, v34
	v_and_b32_e32 v61, 0xffff0000, v34
	v_lshlrev_b32_e32 v54, 16, v31
	v_and_b32_e32 v55, 0xffff0000, v31
	v_lshlrev_b32_e32 v62, 16, v35
	v_and_b32_e32 v63, 0xffff0000, v35
	v_fma_f32 v48, -v2, v56, v48
	v_fma_f32 v49, -v2, v57, v49
	v_fma_f32 v50, -v2, v58, v50
	v_fma_f32 v51, -v2, v59, v51
	v_fma_f32 v52, -v2, v60, v52
	v_fma_f32 v53, -v2, v61, v53
	v_fma_f32 v54, -v2, v62, v54
	v_fma_f32 v55, -v2, v63, v55
	v_mul_f32_e32 v64, v48, v48
	v_fmac_f32_e32 v64, v49, v49
	v_fmac_f32_e32 v64, v50, v50
	v_fmac_f32_e32 v64, v51, v51
	v_fmac_f32_e32 v64, v52, v52
	v_fmac_f32_e32 v64, v53, v53
	v_fmac_f32_e32 v64, v54, v54
	v_fmac_f32_e32 v64, v55, v55
	s_nop 1
	v_add_f32_dpp v65, v64, v64 quad_perm:[1,0,3,2] row_mask:0xf bank_mask:0xf
	s_nop 1
	v_add_f32_dpp v64, v65, v65 quad_perm:[2,3,0,1] row_mask:0xf bank_mask:0xf
	s_nop 1
	v_add_f32_dpp v65, v64, v64 row_half_mirror row_mask:0xf bank_mask:0xf
	s_nop 1
	v_add_f32_dpp v64, v65, v65 row_mirror row_mask:0xf bank_mask:0xf
	v_fmamk_f32 v65, v64, 0x3c000000, v214
	v_rsq_f32_e32 v66, v65
	s_nop 0
	v_mul_f32_e32 v67, v65, v66
	v_mul_f32_e32 v67, v67, v66
	v_fma_f32 v67, v67, -0.5, v86
	v_mul_f32_e32 v66, v66, v67
	v_mul_f32_e32 v66, 0x3f24fd5c, v66
	v_mul_f32_e32 v68, v66, v24
	v_mul_f32_e32 v69, v66, v25
	v_mul_f32_e32 v70, v66, v26
	v_mul_f32_e32 v71, v66, v27
	v_mul_f32_e32 v72, v66, v20
	v_mul_f32_e32 v73, v66, v21
	v_mul_f32_e32 v74, v66, v22
	v_mul_f32_e32 v75, v66, v23
	v_mul_f32_e32 v48, v48, v68
	v_mul_f32_e32 v49, v49, v69
	v_mul_f32_e32 v50, v50, v70
	v_mul_f32_e32 v51, v51, v71
	v_mul_f32_e32 v52, v52, v72
	v_mul_f32_e32 v53, v53, v73
	v_mul_f32_e32 v54, v54, v74
	v_mul_f32_e32 v55, v55, v75
	v_cvt_pk_bf16_f32 v76, v48, v49
	v_cvt_pk_bf16_f32 v77, v50, v51
	v_cvt_pk_bf16_f32 v78, v52, v53
	v_cvt_pk_bf16_f32 v79, v54, v55
	v_add_co_u32_e32 v84, vcc, 0x8000000, v44
	s_nop 1
	v_addc_co_u32_e32 v85, vcc, 0, v45, vcc
	global_store_dwordx4 v[84:85], v[76:79], off
	s_branch .LBB0_1017
.Lp18_last1:
	v_lshlrev_b32_e32 v48, 16, v36
	v_and_b32_e32 v49, 0xffff0000, v36
	v_lshlrev_b32_e32 v56, 16, v40
	v_and_b32_e32 v57, 0xffff0000, v40
	v_lshlrev_b32_e32 v50, 16, v37
	v_and_b32_e32 v51, 0xffff0000, v37
	v_lshlrev_b32_e32 v58, 16, v41
	v_and_b32_e32 v59, 0xffff0000, v41
	v_lshlrev_b32_e32 v52, 16, v38
	v_and_b32_e32 v53, 0xffff0000, v38
	v_lshlrev_b32_e32 v60, 16, v42
	v_and_b32_e32 v61, 0xffff0000, v42
	v_lshlrev_b32_e32 v54, 16, v39
	v_and_b32_e32 v55, 0xffff0000, v39
	v_lshlrev_b32_e32 v62, 16, v43
	v_and_b32_e32 v63, 0xffff0000, v43
	v_fma_f32 v48, -v2, v56, v48
	v_fma_f32 v49, -v2, v57, v49
	v_fma_f32 v50, -v2, v58, v50
	v_fma_f32 v51, -v2, v59, v51
	v_fma_f32 v52, -v2, v60, v52
	v_fma_f32 v53, -v2, v61, v53
	v_fma_f32 v54, -v2, v62, v54
	v_fma_f32 v55, -v2, v63, v55
	v_mul_f32_e32 v64, v48, v48
	v_fmac_f32_e32 v64, v49, v49
	v_fmac_f32_e32 v64, v50, v50
	v_fmac_f32_e32 v64, v51, v51
	v_fmac_f32_e32 v64, v52, v52
	v_fmac_f32_e32 v64, v53, v53
	v_fmac_f32_e32 v64, v54, v54
	v_fmac_f32_e32 v64, v55, v55
	s_nop 1
	v_add_f32_dpp v65, v64, v64 quad_perm:[1,0,3,2] row_mask:0xf bank_mask:0xf
	s_nop 1
	v_add_f32_dpp v64, v65, v65 quad_perm:[2,3,0,1] row_mask:0xf bank_mask:0xf
	s_nop 1
	v_add_f32_dpp v65, v64, v64 row_half_mirror row_mask:0xf bank_mask:0xf
	s_nop 1
	v_add_f32_dpp v64, v65, v65 row_mirror row_mask:0xf bank_mask:0xf
	v_fmamk_f32 v65, v64, 0x3c000000, v214
	v_rsq_f32_e32 v66, v65
	s_nop 0
	v_mul_f32_e32 v67, v65, v66
	v_mul_f32_e32 v67, v67, v66
	v_fma_f32 v67, v67, -0.5, v86
	v_mul_f32_e32 v66, v66, v67
	v_mul_f32_e32 v66, 0x3f24fd5c, v66
	v_mul_f32_e32 v68, v66, v24
	v_mul_f32_e32 v69, v66, v25
	v_mul_f32_e32 v70, v66, v26
	v_mul_f32_e32 v71, v66, v27
	v_mul_f32_e32 v72, v66, v20
	v_mul_f32_e32 v73, v66, v21
	v_mul_f32_e32 v74, v66, v22
	v_mul_f32_e32 v75, v66, v23
	v_mul_f32_e32 v48, v48, v68
	v_mul_f32_e32 v49, v49, v69
	v_mul_f32_e32 v50, v50, v70
	v_mul_f32_e32 v51, v51, v71
	v_mul_f32_e32 v52, v52, v72
	v_mul_f32_e32 v53, v53, v73
	v_mul_f32_e32 v54, v54, v74
	v_mul_f32_e32 v55, v55, v75
	v_cvt_pk_bf16_f32 v76, v48, v49
	v_cvt_pk_bf16_f32 v77, v50, v51
	v_cvt_pk_bf16_f32 v78, v52, v53
	v_cvt_pk_bf16_f32 v79, v54, v55
	v_add_co_u32_e32 v84, vcc, 0x8000000, v46
	s_nop 1
	v_addc_co_u32_e32 v85, vcc, 0, v47, vcc
	global_store_dwordx4 v[84:85], v[76:79], off
	s_branch .LBB0_1017
